# early acquire; next sb_wait skips both the token poll and the invalidate when the early acquire already observed the token
# baseline (speedup 1.0000x reference)
.LBB0_114:
	s_cmp_lt_i32 s63, 2
	s_cbranch_scc1 .LBB0_132
	v_readlane_b32 s0, v255, 10
	v_readlane_b32 s1, v255, 11
	s_and_b64 vcc, exec, s[0:1]
	s_cbranch_vccnz .LBB0_131
	v_readlane_b32 s32, v255, 56
	s_cmp_eq_u32 s32, 1
	s_cbranch_scc1 .LBB0_131
	v_mbcnt_lo_u32_b32 v0, -1, 0
	v_mbcnt_hi_u32_b32 v0, -1, v0
	s_nop 0
	v_cmp_eq_u32_e32 vcc, 0, v0
	s_and_saveexec_b64 s[4:5], vcc
	s_cbranch_execz .LBB0_130
	s_add_i32 s0, s63, -2
	s_mul_hi_u32 s1, s0, 0x220
	s_mulk_i32 s0, 0x220
	v_readlane_b32 s2, v255, 12
	s_add_u32 s10, s2, s0
	v_readlane_b32 s0, v255, 13
	s_addc_u32 s11, s0, s1
	v_readlane_b32 s0, v255, 17
	s_nop 0
	v_mov_b64_e32 v[2:3], s[10:11]
	v_mov_b32_e32 v0, s0
	ds_read_b32 v0, v0
	flat_load_dword v2, v[2:3] offset:512 sc1
	s_waitcnt vmcnt(0) lgkmcnt(0)
	v_cmp_lt_u32_e32 vcc, v2, v0
	s_and_saveexec_b64 s[8:9], vcc
	s_cbranch_execz .LBB0_129
	s_mov_b32 s0, 1
	s_mov_b64 s[12:13], 0
	s_branch .LBB0_120

.LBB0_180:
	s_cmp_lt_i32 s62, 2
	s_cbranch_scc1 .LBB0_198
	v_readlane_b32 s0, v255, 10
	v_readlane_b32 s1, v255, 11
	s_and_b64 vcc, exec, s[0:1]
	s_cbranch_vccnz .LBB0_197
	v_readlane_b32 s32, v255, 56
	s_cmp_eq_u32 s32, 1
	s_cbranch_scc1 .LBB0_197
	v_mbcnt_lo_u32_b32 v0, -1, 0
	v_mbcnt_hi_u32_b32 v0, -1, v0
	s_nop 0
	v_cmp_eq_u32_e32 vcc, 0, v0
	s_and_saveexec_b64 s[4:5], vcc
	s_cbranch_execz .LBB0_196
	s_add_i32 s0, s62, -2
	s_mul_hi_u32 s1, s0, 0x220
	s_mulk_i32 s0, 0x220
	v_readlane_b32 s2, v255, 12
	s_add_u32 s8, s2, s0
	v_readlane_b32 s0, v255, 13
	s_addc_u32 s9, s0, s1
	v_readlane_b32 s0, v255, 17
	s_nop 0
	v_mov_b64_e32 v[2:3], s[8:9]
	v_mov_b32_e32 v0, s0
	ds_read_b32 v0, v0
	flat_load_dword v2, v[2:3] offset:512 sc1
	s_waitcnt vmcnt(0) lgkmcnt(0)
	v_cmp_lt_u32_e32 vcc, v2, v0
	s_and_saveexec_b64 s[6:7], vcc
	s_cbranch_execz .LBB0_195
	s_mov_b32 s0, 1
	s_mov_b64 s[10:11], 0
	s_branch .LBB0_186

.LBB0_241:
	s_cmp_lt_i32 s63, 2
	s_cbranch_scc1 .LBB0_259
	v_readlane_b32 s0, v255, 10
	v_readlane_b32 s1, v255, 11
	s_and_b64 vcc, exec, s[0:1]
	s_cbranch_vccnz .LBB0_258
	v_readlane_b32 s32, v255, 56
	s_cmp_eq_u32 s32, 1
	s_cbranch_scc1 .LBB0_258
	v_mbcnt_lo_u32_b32 v0, -1, 0
	v_mbcnt_hi_u32_b32 v0, -1, v0
	s_nop 0
	v_cmp_eq_u32_e32 vcc, 0, v0
	s_and_saveexec_b64 s[4:5], vcc
	s_cbranch_execz .LBB0_257
	s_add_i32 s0, s63, -2
	s_mul_hi_u32 s1, s0, 0x220
	s_mulk_i32 s0, 0x220
	v_readlane_b32 s2, v255, 12
	s_add_u32 s10, s2, s0
	v_readlane_b32 s0, v255, 13
	s_addc_u32 s11, s0, s1
	v_readlane_b32 s0, v255, 17
	s_nop 0
	v_mov_b64_e32 v[2:3], s[10:11]
	v_mov_b32_e32 v0, s0
	ds_read_b32 v0, v0
	flat_load_dword v2, v[2:3] offset:512 sc1
	s_waitcnt vmcnt(0) lgkmcnt(0)
	v_cmp_lt_u32_e32 vcc, v2, v0
	s_and_saveexec_b64 s[6:7], vcc
	s_cbranch_execz .LBB0_256
	s_mov_b32 s0, 1
	s_mov_b64 s[12:13], 0
	s_branch .LBB0_247

.LBB0_340:
	s_mov_b32 s26, s63
	s_cmp_lt_i32 s63, 2
	s_cbranch_scc1 .LBB0_358
	v_readlane_b32 s6, v255, 10
	v_readlane_b32 s7, v255, 11
	s_and_b64 vcc, exec, s[6:7]
	s_cbranch_vccnz .LBB0_357
	v_readlane_b32 s32, v255, 56
	s_cmp_eq_u32 s32, 1
	s_cbranch_scc1 .LBB0_357
	v_mbcnt_lo_u32_b32 v0, -1, 0
	v_mbcnt_hi_u32_b32 v0, -1, v0
	s_nop 0
	v_cmp_eq_u32_e32 vcc, 0, v0
	s_and_saveexec_b64 s[6:7], vcc
	s_cbranch_execz .LBB0_356
	s_add_i32 s3, s26, -2
	s_mul_hi_u32 s10, s3, 0x220
	s_mulk_i32 s3, 0x220
	v_readlane_b32 s11, v255, 12
	s_add_u32 s12, s11, s3
	v_readlane_b32 s3, v255, 13
	s_addc_u32 s13, s3, s10
	v_readlane_b32 s3, v255, 17
	s_nop 0
	v_mov_b64_e32 v[2:3], s[12:13]
	v_mov_b32_e32 v0, s3
	ds_read_b32 v0, v0
	flat_load_dword v2, v[2:3] offset:512 sc1
	s_waitcnt vmcnt(0) lgkmcnt(0)
	v_cmp_lt_u32_e32 vcc, v2, v0
	s_and_saveexec_b64 s[10:11], vcc
	s_cbranch_execz .LBB0_355
	s_mov_b32 s3, 1
	s_mov_b64 s[14:15], 0
	s_branch .LBB0_346
